# P7b: every workgroup does one qx tile and one attention item per virtual block (0..127 tile first, 128..255 attention first) instead of half the workgroups doing two of each
# baseline (speedup 1.0000x reference)
; __global__ void __launch_bounds__(512) hymba_fwd(Params p) {
;     ...
;     if (IN_PH(7)) { PH_LOCALS
;         const int ng = G >> 1;
;         if (bid < ng) {
;             for (int t = bid; t < 32 * 8; t += ng) { int nt, mt; tile_map(t, 32, 8, mt, nt);
;                 EpiBfS e{qx + (size_t)mt * 256 * LDB + nt * 256, LDB};
;                 gemm256_tile(hbuf + (size_t)mt * 256 * LDB, LDB, Wt_cq + (size_t)nt * 256 * LDB, LDB, D, lds, e);
;             }
;         } else {
;             const int ob = bid - ng, no = G - ng;
;             for (int t0 = 2 * ob; t0 < 512; t0 += 2 * no) attn_sample_item(p, min(t0 + vb, 511), vlds);
.LBB0_1203:
	s_or_b64 exec, exec, s[4:5]
	s_waitcnt lgkmcnt(0)
	s_barrier
	s_load_dwordx2 s[4:5], s[0:1], 0xd0
	s_waitcnt lgkmcnt(0)
	s_cmp_lt_i32 s4, 8
	s_cselect_b64 s[6:7], -1, 0
	s_cmp_gt_i32 s5, 7
	s_cselect_b64 s[4:5], -1, 0
	s_and_b64 s[4:5], s[6:7], s[4:5]
	s_andn2_b64 vcc, exec, s[4:5]
	s_cbranch_vccnz .LBB0_1240
	v_mov_b32_e32 v1, v0
	s_ashr_i32 s17, s33, 1
	s_sub_i32 s96, s2, s17
	s_sub_i32 s97, s33, s17
	s_mov_b32 s98, s17
	s_mov_b32 s99, 1
	s_cmpk_lg_i32 s33, 0x100
	s_cbranch_scc1 .Lp7b_cfg
	s_mov_b32 s96, s2
	s_movk_i32 s97, 0x100
	s_movk_i32 s98, 0x100
	s_mov_b32 s99, 0
.Lp7b_cfg:
	s_cmp_ge_i32 s2, s17
	v_readfirstlane_b32 s6, v1
	s_mov_b64 s[4:5], -1
	s_cbranch_scc0 .LBB0_1232
.Lp7b_attn:
	s_mov_b32 s4, s96
	s_cmpk_gt_u32 s4, 0xff
	s_movk_i32 s26, 0xff
	s_cbranch_scc1 .LBB0_1231
	s_ashr_i32 s27, s6, 8
	s_load_dwordx2 s[6:7], s[0:1], 0xc8
	s_load_dwordx4 s[8:11], s[0:1], 0x18
	s_lshl_b32 s30, s27, 16
	s_lshl_b32 s31, s4, 1
	s_mov_b32 s4, s97
	s_waitcnt lgkmcnt(0)
	s_add_u32 s34, s6, 0x1cc29000
	v_mbcnt_lo_u32_b32 v2, -1, 0
	s_addc_u32 s35, s7, 0
	v_mbcnt_hi_u32_b32 v90, -1, v2
	s_add_u32 s6, s6, 0x22039000
	v_and_b32_e32 v2, 64, v90
	v_and_b32_e32 v1, 0xff, v0
	s_addc_u32 s7, s7, 0
	s_lshl_b32 s36, s4, 1
	s_or_b32 s37, s30, 0x2000
	s_movk_i32 s38, 0x7ff
	s_mov_b32 s13, 0
	s_movk_i32 s39, 0x1080
	v_mov_b32_e32 v67, 0
	s_mov_b32 s16, 0x3d3504f3
	s_movk_i32 s40, 0x6ff
	s_movk_i32 s41, 0xfc00
	s_mov_b32 s42, 0xff61b1e6
	s_mov_b32 s43, 0x8000
	s_mov_b32 s44, 0xa000
	s_mov_b32 s45, 0xc000
	s_mov_b32 s46, 0xe000
	v_add_u32_e32 v91, 64, v2
	v_xor_b32_e32 v92, 1, v90
	v_xor_b32_e32 v93, 2, v90
	v_xor_b32_e32 v94, 4, v90
	v_xor_b32_e32 v95, 8, v90

; __global__ void __launch_bounds__(512) hymba_fwd(Params p) {
;     ...
;         } else {
;             const int ob = bid - ng, no = G - ng;
;             for (int t0 = 2 * ob; t0 < 512; t0 += 2 * no) attn_sample_item(p, min(t0 + vb, 511), vlds);
.LBB0_1231:
	s_cmp_lg_u32 s99, 0
	s_cbranch_scc1 .Lp7b_a_done
	s_mov_b32 s99, 1
	s_branch .Lp7b_gemm

; __global__ void __launch_bounds__(512) hymba_fwd(Params p) {
;     ...
;         const int ng = G >> 1;
;         if (bid < ng) {
;             for (int t = bid; t < 32 * 8; t += ng) { int nt, mt; tile_map(t, 32, 8, mt, nt);
;                 EpiBfS e{qx + (size_t)mt * 256 * LDB + nt * 256, LDB};
;                 gemm256_tile(hbuf + (size_t)mt * 256 * LDB, LDB, Wt_cq + (size_t)nt * 256 * LDB, LDB, D, lds, e);
.Lp7b_gemm:
	s_cmpk_gt_i32 s2, 0xff
	s_cbranch_scc1 .LBB0_1240
	s_mov_b64 s[4:5], 0x4318080
	v_lshl_add_u64 v[134:135], v[158:159], 0, s[4:5]
	s_mov_b64 s[4:5], 0x2188080
	v_lshl_add_u64 v[136:137], v[158:159], 0, s[4:5]
	v_mov_b32_e32 v1, 0x108000
	s_movk_i32 s16, 0x1080
	v_mov_b32_e32 v139, 0
	s_mov_b64 s[4:5], 0x42000
	s_mov_b64 s[6:7], 0x84000
	s_mov_b64 s[8:9], 0xc6000
	s_movk_i32 s18, 0xff80
	s_mov_b64 s[10:11], 0x80
	s_mov_b32 s19, s2

; template <class Epi>
; DEV void gemm256_tile(const bf16_t* __restrict__ A, int lda, const bf16_t* __restrict__ Bt, int ldb, int K, unsigned char* lds, const Epi& epi) {
;     ...
; #pragma unroll 4
;         for (int i = 0; i < 16; ++i) {
;             const int idx = tid + 512 * i, row = idx >> 5, cp = idx & 31, c = cp ^ (row & 31);
;             const uint4 d = *(const uint4*)(lds + row * 512 + (cp << 4));
;             *(uint4*)(epi.obase + (size_t)row * epi.old + c * 8) = epi.finish(row, c * 8, d);
;         }
;         __syncthreads();
; __global__ void __launch_bounds__(512) hymba_fwd(Params p) {
;     ...
;             for (int t = bid; t < 32 * 8; t += ng) { int nt, mt; tile_map(t, 32, 8, mt, nt);
;                 EpiBfS e{qx + (size_t)mt * 256 * LDB + nt * 256, LDB};
;                 gemm256_tile(hbuf + (size_t)mt * 256 * LDB, LDB, Wt_cq + (size_t)nt * 256 * LDB, LDB, D, lds, e);
;             }
.LBB0_1238:
	v_add_u32_e32 v3, s12, v144
	v_ashrrev_i32_e32 v4, 5, v3
	v_add_u32_e32 v5, 0x200, v3
	v_add_u32_e32 v6, 0x400, v3
	v_add_u32_e32 v3, 0x600, v3
	v_xor_b32_e32 v7, v4, v144
	v_lshl_or_b32 v8, v4, 9, v2
	v_ashrrev_i32_e32 v9, 5, v5
	v_ashrrev_i32_e32 v10, 5, v6
	v_ashrrev_i32_e32 v3, 5, v3
	v_mad_i64_i32 v[20:21], s[20:21], v4, s16, v[26:27]
	v_lshlrev_b32_e32 v11, 4, v7
	ds_read_b128 v[4:7], v8
	v_xor_b32_e32 v8, v9, v144
	v_lshl_or_b32 v12, v9, 9, v2
	v_xor_b32_e32 v13, v10, v144
	v_lshl_or_b32 v14, v10, 9, v2
	v_xor_b32_e32 v15, v3, v144
	v_lshl_or_b32 v16, v3, 9, v2
	v_mad_i64_i32 v[22:23], s[20:21], v9, s16, v[26:27]
	v_mad_i64_i32 v[24:25], s[20:21], v10, s16, v[26:27]
	v_mad_i64_i32 v[28:29], s[20:21], v3, s16, v[26:27]
	v_and_b32_e32 v138, 0x1f0, v11
	v_lshlrev_b32_e32 v3, 4, v8
	ds_read_b128 v[8:11], v12
	v_lshlrev_b32_e32 v30, 4, v13
	v_lshlrev_b32_e32 v31, 4, v15
	ds_read_b128 v[12:15], v14
	ds_read_b128 v[16:19], v16
	v_lshl_add_u64 v[20:21], v[20:21], 0, v[138:139]
	v_and_b32_e32 v138, 0x1f0, v3
	s_addk_i32 s12, 0x800
	v_lshl_add_u64 v[22:23], v[22:23], 0, v[138:139]
	v_and_b32_e32 v138, 0x1f0, v30
	s_cmpk_lg_i32 s12, 0x2000
	v_lshl_add_u64 v[24:25], v[24:25], 0, v[138:139]
	v_and_b32_e32 v138, 0x1f0, v31
	s_waitcnt lgkmcnt(3)
	global_store_dwordx4 v[20:21], v[4:7], off
	s_nop 1
	v_lshl_add_u64 v[4:5], v[28:29], 0, v[138:139]
	s_waitcnt lgkmcnt(2)
	global_store_dwordx4 v[22:23], v[8:11], off
	s_waitcnt lgkmcnt(1)
	global_store_dwordx4 v[24:25], v[12:15], off
	s_waitcnt lgkmcnt(0)
	global_store_dwordx4 v[4:5], v[16:19], off
	s_cbranch_scc1 .LBB0_1238
	s_add_i32 s19, s19, s98
	s_cmpk_gt_i32 s19, 0xff
	s_waitcnt vmcnt(63) expcnt(7) lgkmcnt(15)
	s_barrier
	s_cbranch_scc0 .LBB0_1235
	s_cmp_lg_u32 s99, 0
	s_cbranch_scc1 .LBB0_1240
	s_mov_b32 s99, 1
	v_readfirstlane_b32 s6, v0
	s_branch .Lp7b_attn
